# DMA sub-groups moved one MFMA block further from the barrier (H1: P.V block 1 gaps, H2: QK pairs 2-5)
# speedup vs baseline: 1.0911x; 1.0071x over previous
; #define SBAR() __builtin_amdgcn_sched_barrier(0)
; #define PVE_M(OD, PA, L, H, IDX) do { OD = __builtin_amdgcn_mfma_f32_32x32x16_bf16(PA, PKV(L, H), OD, 0, 0, 0); SBAR(); p[IDX] = __builtin_amdgcn_exp2f(p[IDX]); asm volatile("" : "+v"(p)); SBAR(); } while (0)
; __device__ __forceinline__ void pv_exp(f32x16* o, int vb, bf16x8 pa0, bf16x8 pa1, bf16x8 pa2, bf16x8 pa3, f32x16& p, VF8& fa) {
;   VF8 fb;
;   asm volatile("s_waitcnt lgkmcnt(0)" ::: "memory"); SBAR();
;   PVE_M(o[0], pa0, fa.l0, fa.h0, 0); PVE_M(o[0], pa1, fa.l1, fa.h1, 1); vf8_read<1>(fb, vb); SBAR(); PVE_M(o[0], pa2, fa.l2, fa.h2, 2); PVE_M(o[0], pa3, fa.l3, fa.h3, 3);
;   asm volatile("s_waitcnt lgkmcnt(0)" ::: "memory"); SBAR();
;   PVE_M(o[1], pa0, fb.l0, fb.h0, 4); PVE_M(o[1], pa1, fb.l1, fb.h1, 5); vf8_read<2>(fa, vb); SBAR(); PVE_M(o[1], pa2, fb.l2, fb.h2, 6); PVE_M(o[1], pa3, fb.l3, fb.h3, 7);
;   asm volatile("s_waitcnt lgkmcnt(0)" ::: "memory"); SBAR();
;   PVE_M(o[2], pa0, fa.l0, fa.h0, 8); PVE_M(o[2], pa1, fa.l1, fa.h1, 9); vf8_read<3>(fb, vb); SBAR(); PVE_M(o[2], pa2, fa.l2, fa.h2, 10); PVE_M(o[2], pa3, fa.l3, fa.h3, 11);
;   asm volatile("s_waitcnt lgkmcnt(0)" ::: "memory"); SBAR();
;   PVE_M(o[3], pa0, fb.l0, fb.h0, 12); PVE_M(o[3], pa1, fb.l1, fb.h1, 13); PVE_M(o[3], pa2, fb.l2, fb.h2, 14); PVE_M(o[3], pa3, fb.l3, fb.h3, 15);
; }
.LBB0_457:
	s_waitcnt vmcnt(0)
	s_barrier
	s_waitcnt lgkmcnt(0)
	v_mfma_f32_32x32x16_bf16 v[50:65], v[196:199], v[94:97], v[50:65]
	v_exp_f32_e32 v132, v132
	v_mfma_f32_32x32x16_bf16 v[50:65], v[204:207], v[90:93], v[50:65]
	v_exp_f32_e32 v133, v133
	ds_read_b64_tr_b16 v[90:91], v0 offset:0x200
	ds_read_b64_tr_b16 v[92:93], v0 offset:0xa00
	ds_read_b64_tr_b16 v[94:95], v0 offset:0x1200
	ds_read_b64_tr_b16 v[96:97], v0 offset:0x1a00
	ds_read_b64_tr_b16 v[114:115], v0 offset:0x2200
	ds_read_b64_tr_b16 v[116:117], v0 offset:0x2a00
	ds_read_b64_tr_b16 v[118:119], v0 offset:0x3200
	ds_read_b64_tr_b16 v[120:121], v0 offset:0x3a00
	v_mfma_f32_32x32x16_bf16 v[50:65], v[200:203], v[86:89], v[50:65]
	v_exp_f32_e32 v134, v134
	v_mfma_f32_32x32x16_bf16 v[50:65], v[208:211], v[82:85], v[50:65]
	v_exp_f32_e32 v135, v135
	s_waitcnt lgkmcnt(0)
	v_mfma_f32_32x32x16_bf16 v[34:49], v[196:199], v[90:93], v[34:49]
	v_exp_f32_e32 v136, v136
	s_add_i32 s79, s98, s100
	s_add_i32 m0, s79, 0x4000
	s_add_i32 s79, s79, 0x6000
	global_load_lds_dwordx4 v[180:181], off
	v_mfma_f32_32x32x16_bf16 v[34:49], v[204:207], v[94:97], v[34:49]
	v_exp_f32_e32 v137, v137
	s_mov_b32 m0, s79
	s_add_i32 s79, s98, s101
	global_load_lds_dwordx4 v[182:183], off
	ds_read_b64_tr_b16 v[82:83], v0 offset:0x400
	ds_read_b64_tr_b16 v[84:85], v0 offset:0xc00
	ds_read_b64_tr_b16 v[86:87], v0 offset:0x1400
	ds_read_b64_tr_b16 v[88:89], v0 offset:0x1c00
	ds_read_b64_tr_b16 v[90:91], v0 offset:0x2400
	ds_read_b64_tr_b16 v[92:93], v0 offset:0x2c00
	ds_read_b64_tr_b16 v[94:95], v0 offset:0x3400
	ds_read_b64_tr_b16 v[96:97], v0 offset:0x3c00
	v_mfma_f32_32x32x16_bf16 v[34:49], v[200:203], v[114:117], v[34:49]
	v_exp_f32_e32 v138, v138
	s_mov_b32 m0, s79
	s_add_i32 s79, s79, 0x380
	global_load_lds_dwordx4 v[214:215], off
	v_mfma_f32_32x32x16_bf16 v[34:49], v[208:211], v[118:121], v[34:49]
	v_exp_f32_e32 v139, v139
	s_mov_b32 m0, s79
	s_nop 0
	global_load_lds_dwordx4 v[214:215], off offset:128
	v_lshl_add_u64 v[180:181], v[180:181], 0, s[76:77]
	v_lshl_add_u64 v[182:183], v[182:183], 0, s[76:77]
	v_lshl_add_u64 v[214:215], v[214:215], 0, s[76:77]
	s_waitcnt lgkmcnt(0)
	v_mfma_f32_32x32x16_bf16 v[18:33], v[196:199], v[82:85], v[18:33]
	v_exp_f32_e32 v140, v140
	v_mfma_f32_32x32x16_bf16 v[18:33], v[204:207], v[86:89], v[18:33]
	v_exp_f32_e32 v141, v141
	ds_read_b64_tr_b16 v[82:83], v0 offset:0x600
	ds_read_b64_tr_b16 v[84:85], v0 offset:0xe00
	ds_read_b64_tr_b16 v[86:87], v0 offset:0x1600
	ds_read_b64_tr_b16 v[88:89], v0 offset:0x1e00
	ds_read_b64_tr_b16 v[114:115], v0 offset:0x2600
	ds_read_b64_tr_b16 v[116:117], v0 offset:0x2e00
	ds_read_b64_tr_b16 v[118:119], v0 offset:0x3600
	ds_read_b64_tr_b16 v[120:121], v0 offset:0x3e00
	v_mfma_f32_32x32x16_bf16 v[18:33], v[200:203], v[90:93], v[18:33]
	v_exp_f32_e32 v142, v142
	v_mfma_f32_32x32x16_bf16 v[18:33], v[208:211], v[94:97], v[18:33]
	v_exp_f32_e32 v143, v143
	s_waitcnt lgkmcnt(0)
	v_mfma_f32_32x32x16_bf16 v[2:17], v[196:199], v[82:85], v[2:17]
	v_exp_f32_e32 v144, v144
	v_mfma_f32_32x32x16_bf16 v[2:17], v[204:207], v[86:89], v[2:17]
	v_exp_f32_e32 v145, v145
	v_mfma_f32_32x32x16_bf16 v[2:17], v[200:203], v[114:117], v[2:17]
	v_exp_f32_e32 v146, v146
	v_mfma_f32_32x32x16_bf16 v[2:17], v[208:211], v[118:121], v[2:17]
	v_exp_f32_e32 v147, v147
	v_cmp_gt_f32_e32 vcc, 1.0, v130
	s_cbranch_vccz .LBB0_461
	s_and_saveexec_b64 s[36:37], s[6:7]
	ds_write_b32 v220, v130 offset:128
	s_or_b64 exec, exec, s[36:37]
	s_waitcnt lgkmcnt(0)
	v_add_u32_e32 v94, v213, v212
	ds_read_b128 v[82:85], v94 offset:224
	ds_read_b128 v[86:89], v94 offset:192
	ds_read_b128 v[90:93], v94 offset:160
	ds_read_b128 v[94:97], v94 offset:128
	s_waitcnt lgkmcnt(3)
	v_pk_mul_f32 v[62:63], v[62:63], v[82:83]
	s_waitcnt lgkmcnt(2)
	v_pk_mul_f32 v[58:59], v[58:59], v[86:87]
	s_waitcnt lgkmcnt(1)
	v_pk_mul_f32 v[54:55], v[54:55], v[90:91]
	v_pk_mul_f32 v[64:65], v[64:65], v[84:85]
	v_pk_mul_f32 v[60:61], v[60:61], v[88:89]
	v_pk_mul_f32 v[56:57], v[56:57], v[92:93]
	s_waitcnt lgkmcnt(0)
	v_pk_mul_f32 v[52:53], v[52:53], v[96:97]
	v_pk_mul_f32 v[50:51], v[50:51], v[94:95]
	v_pk_mul_f32 v[46:47], v[46:47], v[82:83]
	v_pk_mul_f32 v[42:43], v[42:43], v[86:87]
	v_pk_mul_f32 v[38:39], v[38:39], v[90:91]
	v_pk_mul_f32 v[48:49], v[48:49], v[84:85]
	v_pk_mul_f32 v[44:45], v[44:45], v[88:89]
	v_pk_mul_f32 v[40:41], v[40:41], v[92:93]
	v_pk_mul_f32 v[36:37], v[36:37], v[96:97]
	v_pk_mul_f32 v[34:35], v[34:35], v[94:95]
	v_pk_mul_f32 v[30:31], v[30:31], v[82:83]
	v_pk_mul_f32 v[26:27], v[26:27], v[86:87]
	v_pk_mul_f32 v[22:23], v[22:23], v[90:91]
	v_pk_mul_f32 v[32:33], v[32:33], v[84:85]
	v_pk_mul_f32 v[28:29], v[28:29], v[88:89]
	v_pk_mul_f32 v[24:25], v[24:25], v[92:93]
	v_pk_mul_f32 v[20:21], v[20:21], v[96:97]
	v_pk_mul_f32 v[18:19], v[18:19], v[94:95]
	v_pk_mul_f32 v[14:15], v[14:15], v[82:83]
	v_pk_mul_f32 v[10:11], v[10:11], v[86:87]
	v_pk_mul_f32 v[6:7], v[6:7], v[90:91]
	v_pk_mul_f32 v[16:17], v[16:17], v[84:85]
	v_pk_mul_f32 v[12:13], v[12:13], v[88:89]
	v_pk_mul_f32 v[8:9], v[8:9], v[92:93]
	v_pk_mul_f32 v[4:5], v[4:5], v[96:97]
	v_pk_mul_f32 v[2:3], v[2:3], v[94:95]

; #define SBAR() __builtin_amdgcn_sched_barrier(0)
; #define PVE_M(OD, PA, L, H, IDX) do { OD = __builtin_amdgcn_mfma_f32_32x32x16_bf16(PA, PKV(L, H), OD, 0, 0, 0); SBAR(); p[IDX] = __builtin_amdgcn_exp2f(p[IDX]); asm volatile("" : "+v"(p)); SBAR(); } while (0)
; __device__ __forceinline__ void pv_exp(f32x16* o, int vb, bf16x8 pa0, bf16x8 pa1, bf16x8 pa2, bf16x8 pa3, f32x16& p, VF8& fa) {
;   VF8 fb;
;   asm volatile("s_waitcnt lgkmcnt(0)" ::: "memory"); SBAR();
;   PVE_M(o[0], pa0, fa.l0, fa.h0, 0); PVE_M(o[0], pa1, fa.l1, fa.h1, 1); vf8_read<1>(fb, vb); SBAR(); PVE_M(o[0], pa2, fa.l2, fa.h2, 2); PVE_M(o[0], pa3, fa.l3, fa.h3, 3);
;   asm volatile("s_waitcnt lgkmcnt(0)" ::: "memory"); SBAR();
;   PVE_M(o[1], pa0, fb.l0, fb.h0, 4); PVE_M(o[1], pa1, fb.l1, fb.h1, 5); vf8_read<2>(fa, vb); SBAR(); PVE_M(o[1], pa2, fb.l2, fb.h2, 6); PVE_M(o[1], pa3, fb.l3, fb.h3, 7);
;   asm volatile("s_waitcnt lgkmcnt(0)" ::: "memory"); SBAR();
;   PVE_M(o[2], pa0, fa.l0, fa.h0, 8); PVE_M(o[2], pa1, fa.l1, fa.h1, 9); vf8_read<3>(fb, vb); SBAR(); PVE_M(o[2], pa2, fa.l2, fa.h2, 10); PVE_M(o[2], pa3, fa.l3, fa.h3, 11);
;   asm volatile("s_waitcnt lgkmcnt(0)" ::: "memory"); SBAR();
;   PVE_M(o[3], pa0, fb.l0, fb.h0, 12); PVE_M(o[3], pa1, fb.l1, fb.h1, 13); PVE_M(o[3], pa2, fb.l2, fb.h2, 14); PVE_M(o[3], pa3, fb.l3, fb.h3, 15);
; }
.LBB0_463:
	s_waitcnt vmcnt(0)
	s_barrier
	s_waitcnt lgkmcnt(0)
	v_mfma_f32_32x32x16_bf16 v[50:65], v[132:135], v[144:147], v[50:65]
	v_exp_f32_e32 v114, v114
	v_mfma_f32_32x32x16_bf16 v[50:65], v[136:139], v[106:109], v[50:65]
	v_exp_f32_e32 v115, v115
	ds_read_b64_tr_b16 v[106:107], v203 offset:0x200
	ds_read_b64_tr_b16 v[108:109], v203 offset:0xa00
	ds_read_b64_tr_b16 v[144:145], v203 offset:0x1200
	ds_read_b64_tr_b16 v[146:147], v203 offset:0x1a00
	ds_read_b64_tr_b16 v[204:205], v203 offset:0x2200
	ds_read_b64_tr_b16 v[206:207], v203 offset:0x2a00
	ds_read_b64_tr_b16 v[208:209], v203 offset:0x3200
	ds_read_b64_tr_b16 v[210:211], v203 offset:0x3a00
	v_mfma_f32_32x32x16_bf16 v[50:65], v[196:199], v[102:105], v[50:65]
	v_exp_f32_e32 v116, v116
	v_mfma_f32_32x32x16_bf16 v[50:65], v[140:143], v[98:101], v[50:65]
	v_exp_f32_e32 v117, v117
	s_waitcnt lgkmcnt(0)
	v_mfma_f32_32x32x16_bf16 v[34:49], v[132:135], v[106:109], v[34:49]
	v_exp_f32_e32 v118, v118
	s_add_i32 s79, s97, s100
	s_add_i32 m0, s79, 0x4000
	s_add_i32 s79, s79, 0x6000
	global_load_lds_dwordx4 v[180:181], off
	v_mfma_f32_32x32x16_bf16 v[34:49], v[136:139], v[144:147], v[34:49]
	v_exp_f32_e32 v119, v119
	s_mov_b32 m0, s79
	s_add_i32 s79, s97, s101
	global_load_lds_dwordx4 v[182:183], off
	ds_read_b64_tr_b16 v[98:99], v203 offset:0x400
	ds_read_b64_tr_b16 v[100:101], v203 offset:0xc00
	ds_read_b64_tr_b16 v[102:103], v203 offset:0x1400
	ds_read_b64_tr_b16 v[104:105], v203 offset:0x1c00
	ds_read_b64_tr_b16 v[106:107], v203 offset:0x2400
	ds_read_b64_tr_b16 v[108:109], v203 offset:0x2c00
	ds_read_b64_tr_b16 v[144:145], v203 offset:0x3400
	ds_read_b64_tr_b16 v[146:147], v203 offset:0x3c00
	v_mfma_f32_32x32x16_bf16 v[34:49], v[196:199], v[204:207], v[34:49]
	v_exp_f32_e32 v120, v120
	s_mov_b32 m0, s79
	s_add_i32 s79, s79, 0x380
	global_load_lds_dwordx4 v[214:215], off
	v_mfma_f32_32x32x16_bf16 v[34:49], v[140:143], v[208:211], v[34:49]
	v_exp_f32_e32 v121, v121
	s_mov_b32 m0, s79
	s_nop 0
	global_load_lds_dwordx4 v[214:215], off offset:128
	v_lshl_add_u64 v[180:181], v[180:181], 0, s[76:77]
	v_lshl_add_u64 v[182:183], v[182:183], 0, s[76:77]
	v_lshl_add_u64 v[214:215], v[214:215], 0, s[76:77]
	s_waitcnt lgkmcnt(0)
	v_mfma_f32_32x32x16_bf16 v[18:33], v[132:135], v[98:101], v[18:33]
	v_exp_f32_e32 v122, v122
	v_mfma_f32_32x32x16_bf16 v[18:33], v[136:139], v[102:105], v[18:33]
	v_exp_f32_e32 v123, v123
	ds_read_b64_tr_b16 v[98:99], v203 offset:0x600
	ds_read_b64_tr_b16 v[100:101], v203 offset:0xe00
	ds_read_b64_tr_b16 v[102:103], v203 offset:0x1600
	ds_read_b64_tr_b16 v[104:105], v203 offset:0x1e00
	ds_read_b64_tr_b16 v[204:205], v203 offset:0x2600
	ds_read_b64_tr_b16 v[206:207], v203 offset:0x2e00
	ds_read_b64_tr_b16 v[208:209], v203 offset:0x3600
	ds_read_b64_tr_b16 v[210:211], v203 offset:0x3e00
	v_mfma_f32_32x32x16_bf16 v[18:33], v[196:199], v[106:109], v[18:33]
	v_exp_f32_e32 v124, v124
	v_mfma_f32_32x32x16_bf16 v[18:33], v[140:143], v[144:147], v[18:33]
	v_exp_f32_e32 v125, v125
	s_waitcnt lgkmcnt(0)
	v_mfma_f32_32x32x16_bf16 v[2:17], v[132:135], v[98:101], v[2:17]
	v_exp_f32_e32 v126, v126
	v_mfma_f32_32x32x16_bf16 v[2:17], v[136:139], v[102:105], v[2:17]
	v_exp_f32_e32 v127, v127
	v_mfma_f32_32x32x16_bf16 v[2:17], v[196:199], v[204:207], v[2:17]
	v_exp_f32_e32 v128, v128
	v_mfma_f32_32x32x16_bf16 v[2:17], v[140:143], v[208:211], v[2:17]
	v_exp_f32_e32 v129, v129
	v_cmp_gt_f32_e32 vcc, 1.0, v200
	s_cbranch_vccz .LBB0_467
	s_and_saveexec_b64 s[36:37], s[6:7]
	ds_write_b32 v220, v200 offset:128
	s_or_b64 exec, exec, s[36:37]
	s_waitcnt lgkmcnt(0)
	v_add_u32_e32 v110, v213, v212
	ds_read_b128 v[98:101], v110 offset:224
	ds_read_b128 v[102:105], v110 offset:192
	ds_read_b128 v[106:109], v110 offset:160
	ds_read_b128 v[132:135], v110 offset:128
	s_waitcnt lgkmcnt(3)
	v_pk_mul_f32 v[62:63], v[62:63], v[98:99]
	s_waitcnt lgkmcnt(2)
	v_pk_mul_f32 v[58:59], v[58:59], v[102:103]
	s_waitcnt lgkmcnt(1)
	v_pk_mul_f32 v[54:55], v[54:55], v[106:107]
	v_pk_mul_f32 v[64:65], v[64:65], v[100:101]
	v_pk_mul_f32 v[60:61], v[60:61], v[104:105]
	v_pk_mul_f32 v[56:57], v[56:57], v[108:109]
	s_waitcnt lgkmcnt(0)
	v_pk_mul_f32 v[52:53], v[52:53], v[134:135]
	v_pk_mul_f32 v[50:51], v[50:51], v[132:133]
	v_pk_mul_f32 v[46:47], v[46:47], v[98:99]
	v_pk_mul_f32 v[42:43], v[42:43], v[102:103]
	v_pk_mul_f32 v[38:39], v[38:39], v[106:107]
	v_pk_mul_f32 v[48:49], v[48:49], v[100:101]
	v_pk_mul_f32 v[44:45], v[44:45], v[104:105]
	v_pk_mul_f32 v[40:41], v[40:41], v[108:109]
	v_pk_mul_f32 v[36:37], v[36:37], v[134:135]
	v_pk_mul_f32 v[34:35], v[34:35], v[132:133]
	v_pk_mul_f32 v[30:31], v[30:31], v[98:99]
	v_pk_mul_f32 v[26:27], v[26:27], v[102:103]
	v_pk_mul_f32 v[22:23], v[22:23], v[106:107]
	v_pk_mul_f32 v[32:33], v[32:33], v[100:101]
	v_pk_mul_f32 v[28:29], v[28:29], v[104:105]
	v_pk_mul_f32 v[24:25], v[24:25], v[108:109]
	v_pk_mul_f32 v[20:21], v[20:21], v[134:135]
	v_pk_mul_f32 v[18:19], v[18:19], v[132:133]
	v_pk_mul_f32 v[14:15], v[14:15], v[98:99]
	v_pk_mul_f32 v[10:11], v[10:11], v[102:103]
	v_pk_mul_f32 v[6:7], v[6:7], v[106:107]
	v_pk_mul_f32 v[16:17], v[16:17], v[100:101]
	v_pk_mul_f32 v[12:13], v[12:13], v[104:105]
	v_pk_mul_f32 v[8:9], v[8:9], v[108:109]
	v_pk_mul_f32 v[4:5], v[4:5], v[134:135]
	v_pk_mul_f32 v[2:3], v[2:3], v[132:133]

; #define SBAR() __builtin_amdgcn_sched_barrier(0)
; __device__ __forceinline__ unsigned cvtpk(float lo, float hi) { unsigned r; asm volatile("v_cvt_pk_bf16_f32 %0, %1, %2" : "=v"(r) : "v"(lo), "v"(hi)); return r; }
; __device__ __forceinline__ void qkt_fin(f32x16& n0, f32x16& n1, const bf16_t* Ks, const bf16x8* qr, const f32x16& negm, int r32, int hi, ...
;   float psa = 0.f, psb = 0.f; u32x4 wa, wb, wc, wd;
;     ...
; #pragma unroll
;   for (int d0 = 0; d0 < 8; ++d0) { int cb = (d0 * 16 + hi * 8) * 2;
;     bf16x8 b0 = *reinterpret_cast<const bf16x8*>((const char*)Ks + KSWZ(r32, cb));
;     bf16x8 b1 = *reinterpret_cast<const bf16x8*>((const char*)Ks + KSWZ(32 + r32, cb));
;     SBAR(); if (d0 == 0) n0 = __builtin_amdgcn_mfma_f32_32x32x16_bf16(b0, qr[0], negm, 0, 0, 0); else n0 = __builtin_amdgcn_mfma_f32_32x32x16_bf16(b0, qr[d0], n0, 0, 0, 0);
;     SBAR(); QF_CHUNK(2 * d0); SBAR();
;     if (d0 == 0) n1 = __builtin_amdgcn_mfma_f32_32x32x16_bf16(b1, qr[0], negm, 0, 0, 0); else n1 = __builtin_amdgcn_mfma_f32_32x32x16_bf16(b1, qr[d0], n1, 0, 0, 0);
;     SBAR(); QF_CHUNK(2 * d0 + 1); SBAR();
;     if (d0 == 7) { vf8_read<0>(vf0, vbv); SBAR(); } }
;     ...
;   psb += P1[15]; wd[3] = cvtpk(P1[14], P1[15]);
;   l_reg = l_reg * alpha + (psa + psb);
;   pa0 = *reinterpret_cast<bf16x8*>(&wa); pa1 = *reinterpret_cast<bf16x8*>(&wb); pa2 = *reinterpret_cast<bf16x8*>(&wc); pa3 = *reinterpret_cast<bf16x8*>(&wd);
; }
.Lh2_453:
	s_add_i32 s97, s96, 0xffff8000
	s_xor_b32 s98, s96, 0x10000
	s_add_i32 s99, s96, 0x8000
	s_and_b32 s99, s99, 0x18000
	v_add_u32_e32 v196, s96, v236
	ds_read_b128 v[98:101], v196 offset:16384
	ds_read_b128 v[196:199], v196 offset:24576
	v_add_u32_e32 v252, s96, v237
	ds_read_b128 v[248:251], v252 offset:16384
	ds_read_b128 v[252:255], v252 offset:24576
	v_add_u32_e32 v0, s97, v235
	s_waitcnt lgkmcnt(3)
	v_mfma_f32_32x32x16_bf16 v[132:147], v[98:101], v[152:155], v[66:81]
	v_exp_f32_e32 v82, v82
	s_waitcnt lgkmcnt(2)
	v_mfma_f32_32x32x16_bf16 v[98:113], v[196:199], v[152:155], v[66:81]
	v_exp_f32_e32 v83, v83
	v_add_f32_e32 v245, v115, v114
	v_cvt_pk_bf16_f32 v196, v114, v115
	v_add_u32_e32 v206, s96, v238
	ds_read_b128 v[202:205], v206 offset:16384
	ds_read_b128 v[206:209], v206 offset:24576
	s_waitcnt lgkmcnt(3)
	v_mfma_f32_32x32x16_bf16 v[132:147], v[248:251], v[160:163], v[132:147]
	v_exp_f32_e32 v84, v84
	v_add_f32_e32 v245, v116, v245
	v_add_f32_e32 v246, v82, v83
	s_waitcnt lgkmcnt(2)
	v_mfma_f32_32x32x16_bf16 v[98:113], v[252:255], v[160:163], v[98:113]
	v_exp_f32_e32 v85, v85
	v_add_f32_e32 v245, v117, v245
	v_add_f32_e32 v246, v246, v84
	v_cvt_pk_bf16_f32 v197, v116, v117
	v_cvt_pk_bf16_f32 v200, v82, v83
	v_add_u32_e32 v252, s96, v239
	ds_read_b128 v[248:251], v252 offset:16384
	ds_read_b128 v[252:255], v252 offset:24576
	s_add_i32 s79, s99, s100
	s_add_i32 m0, s79, 0x4000
	s_add_i32 s79, s79, 0x6000
	global_load_lds_dwordx4 v[180:181], off
	s_waitcnt lgkmcnt(3)
	v_mfma_f32_32x32x16_bf16 v[132:147], v[202:205], v[148:151], v[132:147]
	v_exp_f32_e32 v86, v86
	v_add_f32_e32 v245, v118, v245
	v_add_f32_e32 v246, v246, v85
	s_waitcnt lgkmcnt(2)
	v_mfma_f32_32x32x16_bf16 v[98:113], v[206:209], v[148:151], v[98:113]
	v_exp_f32_e32 v87, v87
	v_add_f32_e32 v245, v119, v245
	v_add_f32_e32 v246, v246, v86
	v_cvt_pk_bf16_f32 v198, v118, v119
	v_cvt_pk_bf16_f32 v201, v84, v85
	v_add_u32_e32 v208, s96, v240
	ds_read_b128 v[204:207], v208 offset:16384
	ds_read_b128 v[208:211], v208 offset:24576
	s_mov_b32 m0, s79
	s_add_i32 s79, s99, s101
	global_load_lds_dwordx4 v[182:183], off
	s_waitcnt lgkmcnt(3)
	v_mfma_f32_32x32x16_bf16 v[132:147], v[248:251], v[156:159], v[132:147]
	v_exp_f32_e32 v88, v88
	v_add_f32_e32 v245, v120, v245
	v_add_f32_e32 v246, v246, v87
	s_waitcnt lgkmcnt(2)
	v_mfma_f32_32x32x16_bf16 v[98:113], v[252:255], v[156:159], v[98:113]
	v_exp_f32_e32 v89, v89
	v_add_f32_e32 v245, v121, v245
	v_add_f32_e32 v246, v246, v88
	v_cvt_pk_bf16_f32 v199, v120, v121
	v_cvt_pk_bf16_f32 v202, v86, v87
	v_add_u32_e32 v252, s96, v241
	ds_read_b128 v[248:251], v252 offset:16384
	ds_read_b128 v[252:255], v252 offset:24576
	s_mov_b32 m0, s79
	s_add_i32 s79, s79, 0x380
	global_load_lds_dwordx4 v[214:215], off
	s_waitcnt lgkmcnt(3)
	v_mfma_f32_32x32x16_bf16 v[132:147], v[204:207], v[168:171], v[132:147]
	v_exp_f32_e32 v90, v90
	v_add_f32_e32 v245, v122, v245
	v_add_f32_e32 v246, v246, v89
	s_waitcnt lgkmcnt(2)
	v_mfma_f32_32x32x16_bf16 v[98:113], v[208:211], v[168:171], v[98:113]
	v_exp_f32_e32 v91, v91
	v_add_f32_e32 v245, v123, v245
	v_add_f32_e32 v246, v246, v90
	v_cvt_pk_bf16_f32 v204, v122, v123
	v_cvt_pk_bf16_f32 v203, v88, v89
	v_add_u32_e32 v118, s96, v242
	ds_read_b128 v[114:117], v118 offset:16384
	ds_read_b128 v[118:121], v118 offset:24576
	s_mov_b32 m0, s79
	s_nop 0
	global_load_lds_dwordx4 v[214:215], off offset:128
	v_lshl_add_u64 v[180:181], v[180:181], 0, s[76:77]
	v_lshl_add_u64 v[182:183], v[182:183], 0, s[76:77]
	v_lshl_add_u64 v[214:215], v[214:215], 0, s[76:77]
	s_waitcnt lgkmcnt(3)
	v_mfma_f32_32x32x16_bf16 v[132:147], v[248:251], v[176:179], v[132:147]
	v_exp_f32_e32 v92, v92
	v_add_f32_e32 v245, v124, v245
	v_add_f32_e32 v246, v246, v91
	s_waitcnt lgkmcnt(2)
	v_mfma_f32_32x32x16_bf16 v[98:113], v[252:255], v[176:179], v[98:113]
	v_exp_f32_e32 v93, v93
	v_add_f32_e32 v245, v125, v245
	v_add_f32_e32 v246, v246, v92
	v_cvt_pk_bf16_f32 v205, v124, v125
	v_cvt_pk_bf16_f32 v208, v90, v91
	v_add_u32_e32 v252, s96, v243
	ds_read_b128 v[248:251], v252 offset:16384
	ds_read_b128 v[252:255], v252 offset:24576
	s_waitcnt lgkmcnt(3)
	v_mfma_f32_32x32x16_bf16 v[132:147], v[114:117], v[164:167], v[132:147]
	v_exp_f32_e32 v94, v94
	v_add_f32_e32 v245, v126, v245
	v_add_f32_e32 v246, v246, v93
	s_waitcnt lgkmcnt(2)
	v_mfma_f32_32x32x16_bf16 v[98:113], v[118:121], v[164:167], v[98:113]
	v_exp_f32_e32 v95, v95
	v_add_f32_e32 v245, v127, v245
	v_add_f32_e32 v246, v246, v94
	v_cvt_pk_bf16_f32 v206, v126, v127
	v_cvt_pk_bf16_f32 v209, v92, v93
	s_waitcnt lgkmcnt(1)
	v_mfma_f32_32x32x16_bf16 v[132:147], v[248:251], v[172:175], v[132:147]
	v_exp_f32_e32 v96, v96
	v_add_f32_e32 v245, v128, v245
	v_add_f32_e32 v246, v246, v95
	s_waitcnt lgkmcnt(0)
	v_mfma_f32_32x32x16_bf16 v[98:113], v[252:255], v[172:175], v[98:113]
	v_exp_f32_e32 v97, v97
	v_add_f32_e32 v245, v129, v245
	v_add_f32_e32 v246, v246, v96
	v_cvt_pk_bf16_f32 v207, v128, v129
	v_cvt_pk_bf16_f32 v210, v94, v95
	v_mov_b32_e32 v131, v97
	v_cvt_pk_bf16_f32 v211, v96, v97
	ds_read_b64_tr_b16 v[94:95], v0 offset:0
	ds_read_b64_tr_b16 v[96:97], v0 offset:2048
	ds_read_b64_tr_b16 v[90:91], v0 offset:4096
	ds_read_b64_tr_b16 v[92:93], v0 offset:6144
	ds_read_b64_tr_b16 v[86:87], v0 offset:8192
	ds_read_b64_tr_b16 v[88:89], v0 offset:10240
	ds_read_b64_tr_b16 v[82:83], v0 offset:12288
	ds_read_b64_tr_b16 v[84:85], v0 offset:14336
	v_cndmask_b32_e64 v114, 0, 1, s[0:1]
	v_cmp_ne_u32_e64 s[8:9], 1, v114
	s_andn2_b64 vcc, exec, s[0:1]
	s_cbranch_vccnz .Lh2_456
; template <bool FIRST, bool DOEXP = true>
; __device__ __forceinline__ void partialSM(f32x16& p0, f32x16& p1, float& m_reg, f32x16& negm, float& alpha, const bool track = true) {
;     ...
;   float pmax = p0[0];
; #pragma unroll
;   for (int r = 1; r < 16; ++r) pmax = fmaxf(pmax, p0[r]);
; #pragma unroll
;   for (int r = 0; r < 16; ++r) pmax = fmaxf(pmax, p1[r]);
;   { auto rr = __builtin_amdgcn_permlane32_swap(__float_as_uint(pmax), __float_as_uint(pmax), false, false);
;     pmax = fmaxf(__uint_as_float(rr[0]), __uint_as_float(rr[1])); }
;   if (!FIRST && __builtin_expect(__all(pmax <= THRL), 1)) { alpha = 1.f; }
;   else { const float dl = FIRST ? pmax : fmaxf(pmax, 0.f); m_reg += dl; alpha = FIRST ? 1.f : __builtin_amdgcn_exp2f(-dl);
; #pragma unroll
;     for (int r = 0; r < 16; ++r) { p0[r] -= dl; p1[r] -= dl; }
; #pragma unroll
;     for (int r = 0; r < 16; ++r) negm[r] = -m_reg;
;     asm volatile("" : "+v"(negm)); }
	v_max_f32_e32 v114, v133, v133
	v_max_f32_e32 v115, v132, v132
	v_max_f32_e32 v114, v115, v114
	v_max3_f32 v114, v114, v134, v135
	v_max3_f32 v114, v114, v136, v137
	v_max3_f32 v114, v114, v138, v139
	v_max3_f32 v114, v114, v140, v141
	v_max3_f32 v114, v114, v142, v143
	v_max3_f32 v114, v114, v144, v145
	v_max3_f32 v114, v114, v146, v147
	v_max3_f32 v114, v114, v98, v99
	v_max3_f32 v114, v114, v100, v101
	v_max3_f32 v114, v114, v102, v103
	v_max3_f32 v114, v114, v104, v105
	v_max3_f32 v114, v114, v106, v107
	v_max3_f32 v114, v114, v108, v109
	v_max3_f32 v114, v114, v110, v111
	v_max3_f32 v114, v114, v112, v113
	v_mov_b32_e32 v115, v114
	s_nop 1
	v_permlane32_swap_b32_e32 v114, v115
	v_max_f32_e32 v115, v115, v115
	v_max_f32_e32 v114, v114, v114
	v_max_f32_e32 v114, v114, v115
	v_cmp_ge_f32_e32 vcc, s69, v114
	s_cmp_eq_u64 vcc, exec
	v_mov_b32_e32 v130, 1.0
	s_cbranch_scc1 .Lh2_457
	v_max_f32_e32 v66, v114, v114
	v_max_f32_e32 v66, 0, v66
	v_exp_f32_e64 v130, -v66
	v_add_f32_e32 v222, v222, v66
	v_sub_f32_e32 v147, v147, v66
	v_sub_f32_e32 v146, v146, v66
	v_sub_f32_e32 v145, v145, v66
	v_sub_f32_e32 v144, v144, v66
	v_sub_f32_e32 v143, v143, v66
	v_sub_f32_e32 v142, v142, v66
	v_sub_f32_e32 v141, v141, v66
	v_sub_f32_e32 v140, v140, v66
	v_sub_f32_e32 v139, v139, v66
	v_sub_f32_e32 v138, v138, v66
	v_sub_f32_e32 v137, v137, v66
	v_sub_f32_e32 v136, v136, v66
	v_sub_f32_e32 v135, v135, v66
	v_sub_f32_e32 v134, v134, v66
	v_sub_f32_e32 v133, v133, v66
	v_sub_f32_e32 v132, v132, v66
	v_sub_f32_e32 v113, v113, v66
	v_sub_f32_e32 v112, v112, v66
	v_sub_f32_e32 v111, v111, v66
	v_sub_f32_e32 v110, v110, v66
	v_sub_f32_e32 v109, v109, v66
	v_sub_f32_e32 v108, v108, v66
	v_sub_f32_e32 v107, v107, v66
	v_sub_f32_e32 v106, v106, v66
	v_sub_f32_e32 v105, v105, v66
	v_sub_f32_e32 v104, v104, v66
	v_sub_f32_e32 v103, v103, v66
	v_sub_f32_e32 v102, v102, v66
	v_sub_f32_e32 v101, v101, v66
	v_sub_f32_e32 v100, v100, v66
	v_sub_f32_e32 v99, v99, v66
	v_sub_f32_e32 v98, v98, v66
	v_xor_b32_e32 v66, 0x80000000, v222
	v_mov_b32_e32 v67, v66
	v_mov_b32_e32 v68, v66
	v_mov_b32_e32 v69, v66
	v_mov_b32_e32 v70, v66
	v_mov_b32_e32 v71, v66
	v_mov_b32_e32 v72, v66
	v_mov_b32_e32 v73, v66
	v_mov_b32_e32 v74, v66
	v_mov_b32_e32 v75, v66
	v_mov_b32_e32 v76, v66
	v_mov_b32_e32 v77, v66
	v_mov_b32_e32 v78, v66
	v_mov_b32_e32 v79, v66
	v_mov_b32_e32 v80, v66
	v_mov_b32_e32 v81, v66
	s_branch .Lh2_457

; #define SBAR() __builtin_amdgcn_sched_barrier(0)
; __device__ __forceinline__ unsigned cvtpk(float lo, float hi) { unsigned r; asm volatile("v_cvt_pk_bf16_f32 %0, %1, %2" : "=v"(r) : "v"(lo), "v"(hi)); return r; }
; template <bool FIRST, bool DOEXP = true>
; __device__ __forceinline__ void partialSM(f32x16& p0, f32x16& p1, float& m_reg, f32x16& negm, float& alpha, const bool track = true) {
;     ...
;   float pmax = p0[0];
; #pragma unroll
;   for (int r = 1; r < 16; ++r) pmax = fmaxf(pmax, p0[r]);
; #pragma unroll
;   for (int r = 0; r < 16; ++r) pmax = fmaxf(pmax, p1[r]);
;   { auto rr = __builtin_amdgcn_permlane32_swap(__float_as_uint(pmax), __float_as_uint(pmax), false, false);
;     pmax = fmaxf(__uint_as_float(rr[0]), __uint_as_float(rr[1])); }
;   if (!FIRST && __builtin_expect(__all(pmax <= THRL), 1)) { alpha = 1.f; }
; __device__ __forceinline__ void qkt_fin(f32x16& n0, f32x16& n1, const bf16_t* Ks, const bf16x8* qr, const f32x16& negm, int r32, int hi, ...
;   float psa = 0.f, psb = 0.f; u32x4 wa, wb, wc, wd;
;     ...
; #pragma unroll
;   for (int d0 = 0; d0 < 8; ++d0) { int cb = (d0 * 16 + hi * 8) * 2;
;     bf16x8 b0 = *reinterpret_cast<const bf16x8*>((const char*)Ks + KSWZ(r32, cb));
;     bf16x8 b1 = *reinterpret_cast<const bf16x8*>((const char*)Ks + KSWZ(32 + r32, cb));
;     SBAR(); if (d0 == 0) n0 = __builtin_amdgcn_mfma_f32_32x32x16_bf16(b0, qr[0], negm, 0, 0, 0); else n0 = __builtin_amdgcn_mfma_f32_32x32x16_bf16(b0, qr[d0], n0, 0, 0, 0);
;     SBAR(); QF_CHUNK(2 * d0); SBAR();
;     if (d0 == 0) n1 = __builtin_amdgcn_mfma_f32_32x32x16_bf16(b1, qr[0], negm, 0, 0, 0); else n1 = __builtin_amdgcn_mfma_f32_32x32x16_bf16(b1, qr[d0], n1, 0, 0, 0);
;     SBAR(); QF_CHUNK(2 * d0 + 1); SBAR();
;     if (d0 == 7) { vf8_read<0>(vf0, vbv); SBAR(); } }
;     ...
;   psb += P1[15]; wd[3] = cvtpk(P1[14], P1[15]);
;   l_reg = l_reg * alpha + (psa + psb);
;   pa0 = *reinterpret_cast<bf16x8*>(&wa); pa1 = *reinterpret_cast<bf16x8*>(&wb); pa2 = *reinterpret_cast<bf16x8*>(&wc); pa3 = *reinterpret_cast<bf16x8*>(&wd);
; }
.Lh2_461:
	s_waitcnt lgkmcnt(0)
	s_waitcnt vmcnt(0)
	s_barrier
	v_add_u32_e32 v208, s99, v236
	ds_read_b128 v[204:207], v208 offset:16384
	ds_read_b128 v[208:211], v208 offset:24576
	v_add_u32_e32 v252, s99, v237
	ds_read_b128 v[248:251], v252 offset:16384
	ds_read_b128 v[252:255], v252 offset:24576
	v_add_u32_e32 v203, s96, v235
	s_waitcnt lgkmcnt(3)
	v_mfma_f32_32x32x16_bf16 v[114:129], v[204:207], v[152:155], v[66:81]
	v_exp_f32_e32 v98, v98
	s_waitcnt lgkmcnt(2)
	v_mfma_f32_32x32x16_bf16 v[82:97], v[208:211], v[152:155], v[66:81]
	v_exp_f32_e32 v99, v99
	v_add_f32_e32 v201, v133, v132
	v_cvt_pk_bf16_f32 v132, v132, v133
	v_add_u32_e32 v208, s99, v238
	ds_read_b128 v[204:207], v208 offset:16384
	ds_read_b128 v[208:211], v208 offset:24576
	s_waitcnt lgkmcnt(3)
	v_mfma_f32_32x32x16_bf16 v[114:129], v[248:251], v[160:163], v[114:129]
	v_exp_f32_e32 v100, v100
	v_add_f32_e32 v201, v134, v201
	v_add_f32_e32 v202, v98, v99
	s_waitcnt lgkmcnt(2)
	v_mfma_f32_32x32x16_bf16 v[82:97], v[252:255], v[160:163], v[82:97]
	v_exp_f32_e32 v101, v101
	v_add_f32_e32 v201, v135, v201
	v_add_f32_e32 v202, v202, v100
	v_cvt_pk_bf16_f32 v133, v134, v135
	v_cvt_pk_bf16_f32 v196, v98, v99
	v_add_u32_e32 v252, s99, v239
	ds_read_b128 v[248:251], v252 offset:16384
	ds_read_b128 v[252:255], v252 offset:24576
	s_add_i32 s79, s98, s100
	s_add_i32 m0, s79, 0x4000
	s_add_i32 s79, s79, 0x6000
	global_load_lds_dwordx4 v[180:181], off
	s_waitcnt lgkmcnt(3)
	v_mfma_f32_32x32x16_bf16 v[114:129], v[204:207], v[148:151], v[114:129]
	v_exp_f32_e32 v102, v102
	v_add_f32_e32 v201, v136, v201
	v_add_f32_e32 v202, v202, v101
	s_waitcnt lgkmcnt(2)
	v_mfma_f32_32x32x16_bf16 v[82:97], v[208:211], v[148:151], v[82:97]
	v_exp_f32_e32 v103, v103
	v_add_f32_e32 v201, v137, v201
	v_add_f32_e32 v202, v202, v102
	v_cvt_pk_bf16_f32 v134, v136, v137
	v_cvt_pk_bf16_f32 v197, v100, v101
	v_add_u32_e32 v208, s99, v240
	ds_read_b128 v[204:207], v208 offset:16384
	ds_read_b128 v[208:211], v208 offset:24576
	s_mov_b32 m0, s79
	s_add_i32 s79, s98, s101
	global_load_lds_dwordx4 v[182:183], off
	s_waitcnt lgkmcnt(3)
	v_mfma_f32_32x32x16_bf16 v[114:129], v[248:251], v[156:159], v[114:129]
	v_exp_f32_e32 v104, v104
	v_add_f32_e32 v201, v138, v201
	v_add_f32_e32 v202, v202, v103
	s_waitcnt lgkmcnt(2)
	v_mfma_f32_32x32x16_bf16 v[82:97], v[252:255], v[156:159], v[82:97]
	v_exp_f32_e32 v105, v105
	v_add_f32_e32 v201, v139, v201
	v_add_f32_e32 v202, v202, v104
	v_cvt_pk_bf16_f32 v135, v138, v139
	v_cvt_pk_bf16_f32 v198, v102, v103
	v_add_u32_e32 v252, s99, v241
	ds_read_b128 v[248:251], v252 offset:16384
	ds_read_b128 v[252:255], v252 offset:24576
	s_mov_b32 m0, s79
	s_add_i32 s79, s79, 0x380
	global_load_lds_dwordx4 v[214:215], off
	s_waitcnt lgkmcnt(3)
	v_mfma_f32_32x32x16_bf16 v[114:129], v[204:207], v[168:171], v[114:129]
	v_exp_f32_e32 v106, v106
	v_add_f32_e32 v201, v140, v201
	v_add_f32_e32 v202, v202, v105
	s_waitcnt lgkmcnt(2)
	v_mfma_f32_32x32x16_bf16 v[82:97], v[208:211], v[168:171], v[82:97]
	v_exp_f32_e32 v107, v107
	v_add_f32_e32 v201, v141, v201
	v_add_f32_e32 v202, v202, v106
	v_cvt_pk_bf16_f32 v136, v140, v141
	v_cvt_pk_bf16_f32 v199, v104, v105
	v_add_u32_e32 v208, s99, v242
	ds_read_b128 v[204:207], v208 offset:16384
	ds_read_b128 v[208:211], v208 offset:24576
	s_mov_b32 m0, s79
	s_nop 0
	global_load_lds_dwordx4 v[214:215], off offset:128
	v_lshl_add_u64 v[180:181], v[180:181], 0, s[76:77]
	v_lshl_add_u64 v[182:183], v[182:183], 0, s[76:77]
	v_lshl_add_u64 v[214:215], v[214:215], 0, s[76:77]
	s_waitcnt lgkmcnt(3)
	v_mfma_f32_32x32x16_bf16 v[114:129], v[248:251], v[176:179], v[114:129]
	v_exp_f32_e32 v108, v108
	v_add_f32_e32 v201, v142, v201
	v_add_f32_e32 v202, v202, v107
	s_waitcnt lgkmcnt(2)
	v_mfma_f32_32x32x16_bf16 v[82:97], v[252:255], v[176:179], v[82:97]
	v_exp_f32_e32 v109, v109
	v_add_f32_e32 v201, v143, v201
	v_add_f32_e32 v202, v202, v108
	v_cvt_pk_bf16_f32 v137, v142, v143
	v_cvt_pk_bf16_f32 v140, v106, v107
	v_add_u32_e32 v252, s99, v243
	ds_read_b128 v[248:251], v252 offset:16384
	ds_read_b128 v[252:255], v252 offset:24576
	s_waitcnt lgkmcnt(3)
	v_mfma_f32_32x32x16_bf16 v[114:129], v[204:207], v[164:167], v[114:129]
	v_exp_f32_e32 v110, v110
	v_add_f32_e32 v201, v144, v201
	v_add_f32_e32 v202, v202, v109
	s_waitcnt lgkmcnt(2)
	v_mfma_f32_32x32x16_bf16 v[82:97], v[208:211], v[164:167], v[82:97]
	v_exp_f32_e32 v111, v111
	v_add_f32_e32 v201, v145, v201
	v_add_f32_e32 v202, v202, v110
	v_cvt_pk_bf16_f32 v138, v144, v145
	v_cvt_pk_bf16_f32 v141, v108, v109
	s_waitcnt lgkmcnt(1)
	v_mfma_f32_32x32x16_bf16 v[114:129], v[248:251], v[172:175], v[114:129]
	v_exp_f32_e32 v112, v112
	v_add_f32_e32 v201, v146, v201
	v_add_f32_e32 v202, v202, v111
	s_waitcnt lgkmcnt(0)
	v_mfma_f32_32x32x16_bf16 v[82:97], v[252:255], v[172:175], v[82:97]
	v_exp_f32_e32 v113, v113
	v_add_f32_e32 v201, v147, v201
	v_add_f32_e32 v202, v202, v112
	v_cvt_pk_bf16_f32 v139, v146, v147
	v_cvt_pk_bf16_f32 v142, v110, v111
	ds_read_b64_tr_b16 v[144:145], v203 offset:0
	ds_read_b64_tr_b16 v[146:147], v203 offset:2048
	s_nop 0
	ds_read_b64_tr_b16 v[106:107], v203 offset:4096
	ds_read_b64_tr_b16 v[108:109], v203 offset:6144
	ds_read_b64_tr_b16 v[102:103], v203 offset:8192
	ds_read_b64_tr_b16 v[104:105], v203 offset:10240
	ds_read_b64_tr_b16 v[98:99], v203 offset:12288
	ds_read_b64_tr_b16 v[100:101], v203 offset:14336
	v_cvt_pk_bf16_f32 v143, v112, v113
	s_and_b64 vcc, exec, s[8:9]
	v_mov_b32_e32 v200, 1.0
	s_cbranch_vccnz .Lh2_463
	v_max_f32_e32 v110, v115, v115
	v_max_f32_e32 v111, v114, v114
	v_max_f32_e32 v110, v111, v110
	v_max3_f32 v110, v110, v116, v117
	v_max3_f32 v110, v110, v118, v119
	v_max3_f32 v110, v110, v120, v121
	v_max3_f32 v110, v110, v122, v123
	v_max3_f32 v110, v110, v124, v125
	v_max3_f32 v110, v110, v126, v127
	v_max3_f32 v110, v110, v128, v129
	v_max3_f32 v110, v110, v82, v83
	v_max3_f32 v110, v110, v84, v85
	v_max3_f32 v110, v110, v86, v87
	v_max3_f32 v110, v110, v88, v89
	v_max3_f32 v110, v110, v90, v91
	v_max3_f32 v110, v110, v92, v93
	v_max3_f32 v110, v110, v94, v95
	v_max3_f32 v110, v110, v96, v97
	v_mov_b32_e32 v111, v110
	s_nop 1
	v_permlane32_swap_b32_e32 v110, v111
	v_max_f32_e32 v111, v111, v111
	v_max_f32_e32 v110, v110, v110
	v_max_f32_e32 v110, v110, v111
	v_cmp_ge_f32_e32 vcc, s69, v110
	s_cmp_eq_u64 vcc, exec
	v_mov_b32_e32 v200, 1.0
	s_cbranch_scc0 .Lh2_469
